# v54 + q-up rotary epilogue: the 16 rope-table loads hoisted out of the per-row-group load/vmcnt(0)/store chain into dedicated registers, counted vmcnt
# baseline (speedup 1.0000x reference)
; __device__ __forceinline__ u32x2 pack4(f32x4 v) { u32x2 w; w.x = cvtpk(v[0], v[1]); w.y = cvtpk(v[2], v[3]); return w; }
;     __device__ __forceinline__ void operator()(const Acc& acc, const Unit& u, int wr, int wc, int fr, int fq) const {
;     ...
;         const int pn = u.pn, rowb = u.pm * 256 + wr * 64 + fr;
; #pragma unroll
;         for (int ai = 0; ai < 2; ++ai)
; #pragma unroll
;             for (int m = 0; m < 4; ++m) {
;                 const int row = rowb + ai * 128 + m * 16;
;                 const float r = rf[row - row0];
;                 bf16_t* qrow = Qm + (size_t)row * 3072;
;                 if (pn < 8) {
; #pragma unroll
;                     for (int bj = 0; bj < 2; ++bj)
; #pragma unroll
;                         for (int n = 0; n < 2; ++n) *(u32x2*)(qrow + (2 * pn + bj) * 192 + wc * 32 + n * 16 + 4 * fq) = pack4(acc[ai][bj][m][n] * r);
;                 } else {
;                     const int i0 = 16 * (wc & 1) + 4 * fq;
;                     const f32x4 cs = *(const f32x4*)(ropeM + (size_t)row * 64 + i0), sn = *(const f32x4*)(ropeM + (size_t)row * 64 + 32 + i0);
; #pragma unroll
;                     for (int bj = 0; bj < 2; ++bj) { const int head = (pn - 8) * 4 + bj * 2 + (wc >> 1);
;                         const f32x4 x1 = acc[ai][bj][m][0] * r, x2 = acc[ai][bj][m][1] * r;
;                         *(u32x2*)(qrow + head * 192 + 128 + i0) = pack4(x1 * cs - x2 * sn);
;                         *(u32x2*)(qrow + head * 192 + 160 + i0) = pack4(x2 * cs + x1 * sn); }
;                 }
;                 asm volatile("" ::: "memory");
.LBB0_728:
	s_lshl_b32 s2, s16, 8
	s_add_i32 s2, s2, s58
	v_and_or_b32 v4, v183, 15, s2
	v_lshrrev_b32_e32 v2, 2, v183
	v_and_b32_e32 v9, 28, v2
	v_subrev_u32_e32 v2, s62, v4
	v_lshl_add_u32 v2, v2, 2, 0
	s_nop 15
	s_nop 15
	v_add_u32_e32 v2, 0x21000, v2
	ds_read_b32 v8, v2
	s_cmp_gt_i32 s76, 7
	s_cselect_b64 s[40:41], -1, 0
	s_lshl_b32 s2, s76, 2
	v_mov_b64_e32 v[2:3], s[18:19]
	v_add_u32_e32 v7, s60, v9
	s_add_i32 s16, s2, s61
	v_mad_i64_i32 v[10:11], s[2:3], v4, s64, v[2:3]
	v_ashrrev_i32_e32 v5, 31, v4
	s_mov_b64 s[2:3], -1
	s_and_b64 vcc, exec, s[40:41]
	s_mul_i32 s36, s16, 0xc0
	v_lshlrev_b32_e32 v6, 2, v7
	v_lshlrev_b32_e32 v2, 1, v7
	s_cbranch_vccz .LBB0_730
	v_mov_b32_e32 v7, v165
	v_lshlrev_b64 v[250:251], 8, v[4:5]
	v_lshl_add_u64 v[250:251], s[4:5], 0, v[250:251]
	v_mov_b32_e32 v7, v165
	v_lshl_add_u64 v[250:251], v[250:251], 0, v[6:7]
	global_load_dwordx4 v[206:209], v[250:251], off offset:128
	global_load_dwordx4 v[210:213], v[250:251], off
	v_mov_b32_e32 v255, 0
	v_mov_b32_e32 v254, 0x1000
	v_lshl_add_u64 v[252:253], v[250:251], 0, v[254:255]
	global_load_dwordx4 v[214:217], v[252:253], off offset:128
	global_load_dwordx4 v[218:221], v[252:253], off
	v_mov_b32_e32 v255, 0
	v_mov_b32_e32 v254, 0x2000
	v_lshl_add_u64 v[252:253], v[250:251], 0, v[254:255]
	global_load_dwordx4 v[222:225], v[252:253], off offset:128
	global_load_dwordx4 v[226:229], v[252:253], off
	v_mov_b32_e32 v255, 0
	v_mov_b32_e32 v254, 0x3000
	v_lshl_add_u64 v[252:253], v[250:251], 0, v[254:255]
	global_load_dwordx4 v[230:233], v[252:253], off offset:128
	global_load_dwordx4 v[234:237], v[252:253], off
	v_mov_b32_e32 v255, 0
	v_mov_b32_e32 v254, 0x8000
	v_lshl_add_u64 v[252:253], v[250:251], 0, v[254:255]
	global_load_dwordx4 v[238:241], v[252:253], off offset:128
	global_load_dwordx4 v[246:249], v[252:253], off
	s_nop 0
	s_waitcnt lgkmcnt(0)
	v_pk_mul_f32 v[24:25], v[156:157], v[8:9] op_sel_hi:[1,0]
	v_pk_mul_f32 v[26:27], v[154:155], v[8:9] op_sel_hi:[1,0]
	v_pk_mul_f32 v[20:21], v[160:161], v[8:9] op_sel_hi:[1,0]
	v_pk_mul_f32 v[22:23], v[158:159], v[8:9] op_sel_hi:[1,0]
	s_mov_b32 s37, s17
	v_pk_mul_f32 v[28:29], v[152:153], v[8:9] op_sel_hi:[1,0]
	v_pk_mul_f32 v[30:31], v[150:151], v[8:9] op_sel_hi:[1,0]
	v_pk_mul_f32 v[32:33], v[148:149], v[8:9] op_sel_hi:[1,0]
	v_pk_mul_f32 v[168:169], v[146:147], v[8:9] op_sel_hi:[1,0]
	v_mov_b32_e32 v3, v165
	s_add_i32 s16, s36, 0x180
	v_lshl_add_u64 v[170:171], s[36:37], 1, v[10:11]
	v_lshl_add_u64 v[188:189], s[16:17], 1, v[10:11]
	v_lshl_add_u64 v[170:171], v[170:171], 0, v[2:3]
	v_lshl_add_u64 v[188:189], v[188:189], 0, v[2:3]
	s_mov_b64 s[2:3], 0
	s_waitcnt vmcnt(8)
	v_pk_mul_f32 v[190:191], v[24:25], v[208:209]
	v_pk_mul_f32 v[192:193], v[26:27], v[206:207]
	v_pk_mul_f32 v[194:195], v[20:21], v[208:209]
	v_pk_mul_f32 v[196:197], v[22:23], v[206:207]
	v_pk_mul_f32 v[198:199], v[32:33], v[208:209]
	v_pk_mul_f32 v[200:201], v[168:169], v[206:207]
	v_pk_mul_f32 v[14:15], v[28:29], v[208:209]
	v_pk_mul_f32 v[12:13], v[30:31], v[206:207]
	v_pk_fma_f32 v[20:21], v[20:21], v[212:213], v[190:191] neg_lo:[0,0,1] neg_hi:[0,0,1]
	v_pk_fma_f32 v[22:23], v[22:23], v[210:211], v[192:193] neg_lo:[0,0,1] neg_hi:[0,0,1]
	v_pk_fma_f32 v[24:25], v[24:25], v[212:213], v[194:195]
	v_pk_fma_f32 v[26:27], v[26:27], v[210:211], v[196:197]
	v_pk_fma_f32 v[28:29], v[28:29], v[212:213], v[198:199] neg_lo:[0,0,1] neg_hi:[0,0,1]
	v_pk_fma_f32 v[30:31], v[30:31], v[210:211], v[200:201] neg_lo:[0,0,1] neg_hi:[0,0,1]
	v_pk_fma_f32 v[14:15], v[32:33], v[212:213], v[14:15]
	v_pk_fma_f32 v[12:13], v[168:169], v[210:211], v[12:13]
	v_cvt_pk_bf16_f32 v16, v22, v23
	v_cvt_pk_bf16_f32 v17, v20, v21
	v_cvt_pk_bf16_f32 v18, v26, v27
	v_cvt_pk_bf16_f32 v19, v24, v25
	v_cvt_pk_bf16_f32 v20, v30, v31
	v_cvt_pk_bf16_f32 v21, v28, v29
	v_cvt_pk_bf16_f32 v12, v12, v13
	v_cvt_pk_bf16_f32 v13, v14, v15
	v_mov_b32_e32 v255, 0
	v_mov_b32_e32 v254, 0x9000
	v_lshl_add_u64 v[252:253], v[250:251], 0, v[254:255]
	global_load_dwordx4 v[206:209], v[252:253], off offset:128
	global_load_dwordx4 v[210:213], v[252:253], off
	global_store_dwordx2 v[170:171], v[16:17], off offset:256
	global_store_dwordx2 v[170:171], v[18:19], off offset:320
	global_store_dwordx2 v[188:189], v[20:21], off offset:256
	global_store_dwordx2 v[188:189], v[12:13], off offset:320

; __device__ __forceinline__ u32x2 pack4(f32x4 v) { u32x2 w; w.x = cvtpk(v[0], v[1]); w.y = cvtpk(v[2], v[3]); return w; }
;     __device__ __forceinline__ void operator()(const Acc& acc, const Unit& u, int wr, int wc, int fr, int fq) const {
;     ...
;                 } else {
;                     const int i0 = 16 * (wc & 1) + 4 * fq;
;                     const f32x4 cs = *(const f32x4*)(ropeM + (size_t)row * 64 + i0), sn = *(const f32x4*)(ropeM + (size_t)row * 64 + 32 + i0);
; #pragma unroll
;                     for (int bj = 0; bj < 2; ++bj) { const int head = (pn - 8) * 4 + bj * 2 + (wc >> 1);
;                         const f32x4 x1 = acc[ai][bj][m][0] * r, x2 = acc[ai][bj][m][1] * r;
;                         *(u32x2*)(qrow + head * 192 + 128 + i0) = pack4(x1 * cs - x2 * sn);
;                         *(u32x2*)(qrow + head * 192 + 160 + i0) = pack4(x2 * cs + x1 * sn); }
;                 }
.LBB0_732:
	v_or_b32_e32 v12, 16, v4
	v_subrev_u32_e32 v3, s62, v12
	v_lshl_add_u32 v3, v3, 2, 0
	v_add_u32_e32 v3, 0x21000, v3
	s_waitcnt lgkmcnt(0)
	ds_read_b32 v8, v3
	v_mov_b64_e32 v[10:11], s[18:19]
	v_mad_i64_i32 v[10:11], s[2:3], v12, s64, v[10:11]
	v_cndmask_b32_e64 v3, 0, 1, s[40:41]
	v_cmp_ne_u32_e64 s[2:3], 1, v3
	s_andn2_b64 vcc, exec, s[40:41]
	s_mov_b64 s[40:41], -1
	s_cbranch_vccnz .LBB0_734
	v_mov_b32_e32 v7, v165
	s_nop 0
	s_waitcnt lgkmcnt(0)
	v_pk_mul_f32 v[24:25], v[140:141], v[8:9] op_sel_hi:[1,0]
	v_pk_mul_f32 v[26:27], v[138:139], v[8:9] op_sel_hi:[1,0]
	v_pk_mul_f32 v[20:21], v[144:145], v[8:9] op_sel_hi:[1,0]
	v_pk_mul_f32 v[22:23], v[142:143], v[8:9] op_sel_hi:[1,0]
	s_mov_b32 s37, s17
	v_pk_mul_f32 v[28:29], v[136:137], v[8:9] op_sel_hi:[1,0]
	v_pk_mul_f32 v[30:31], v[134:135], v[8:9] op_sel_hi:[1,0]
	v_pk_mul_f32 v[32:33], v[132:133], v[8:9] op_sel_hi:[1,0]
	v_pk_mul_f32 v[146:147], v[130:131], v[8:9] op_sel_hi:[1,0]
	v_mov_b32_e32 v3, v165
	s_add_i32 s16, s36, 0x180
	v_lshl_add_u64 v[148:149], s[36:37], 1, v[10:11]
	v_lshl_add_u64 v[150:151], s[16:17], 1, v[10:11]
	v_lshl_add_u64 v[148:149], v[148:149], 0, v[2:3]
	s_mov_b64 s[40:41], 0
	v_lshl_add_u64 v[150:151], v[150:151], 0, v[2:3]
	s_waitcnt vmcnt(12)
	v_pk_mul_f32 v[152:153], v[24:25], v[216:217]
	v_pk_mul_f32 v[154:155], v[26:27], v[214:215]
	v_pk_mul_f32 v[156:157], v[20:21], v[216:217]
	v_pk_mul_f32 v[158:159], v[22:23], v[214:215]
	v_pk_mul_f32 v[160:161], v[32:33], v[216:217]
	v_pk_mul_f32 v[168:169], v[146:147], v[214:215]
	v_pk_mul_f32 v[14:15], v[28:29], v[216:217]
	v_pk_mul_f32 v[12:13], v[30:31], v[214:215]
	v_pk_fma_f32 v[20:21], v[20:21], v[220:221], v[152:153] neg_lo:[0,0,1] neg_hi:[0,0,1]
	v_pk_fma_f32 v[22:23], v[22:23], v[218:219], v[154:155] neg_lo:[0,0,1] neg_hi:[0,0,1]
	v_pk_fma_f32 v[24:25], v[24:25], v[220:221], v[156:157]
	v_pk_fma_f32 v[26:27], v[26:27], v[218:219], v[158:159]
	v_pk_fma_f32 v[28:29], v[28:29], v[220:221], v[160:161] neg_lo:[0,0,1] neg_hi:[0,0,1]
	v_pk_fma_f32 v[30:31], v[30:31], v[218:219], v[168:169] neg_lo:[0,0,1] neg_hi:[0,0,1]
	v_pk_fma_f32 v[14:15], v[32:33], v[220:221], v[14:15]
	v_pk_fma_f32 v[12:13], v[146:147], v[218:219], v[12:13]
	v_cvt_pk_bf16_f32 v16, v22, v23
	v_cvt_pk_bf16_f32 v17, v20, v21
	v_cvt_pk_bf16_f32 v18, v26, v27
	v_cvt_pk_bf16_f32 v19, v24, v25
	v_cvt_pk_bf16_f32 v20, v30, v31
	v_cvt_pk_bf16_f32 v21, v28, v29
	v_cvt_pk_bf16_f32 v12, v12, v13
	v_cvt_pk_bf16_f32 v13, v14, v15
	v_mov_b32_e32 v255, 0
	v_mov_b32_e32 v254, 0xa000
	v_lshl_add_u64 v[252:253], v[250:251], 0, v[254:255]
	global_load_dwordx4 v[214:217], v[252:253], off offset:128
	global_load_dwordx4 v[218:221], v[252:253], off
	global_store_dwordx2 v[148:149], v[16:17], off offset:256
	global_store_dwordx2 v[148:149], v[18:19], off offset:320
	global_store_dwordx2 v[150:151], v[20:21], off offset:256
	global_store_dwordx2 v[150:151], v[12:13], off offset:320

; __device__ __forceinline__ u32x2 pack4(f32x4 v) { u32x2 w; w.x = cvtpk(v[0], v[1]); w.y = cvtpk(v[2], v[3]); return w; }
;     __device__ __forceinline__ void operator()(const Acc& acc, const Unit& u, int wr, int wc, int fr, int fq) const {
;     ...
;                 } else {
;                     const int i0 = 16 * (wc & 1) + 4 * fq;
;                     const f32x4 cs = *(const f32x4*)(ropeM + (size_t)row * 64 + i0), sn = *(const f32x4*)(ropeM + (size_t)row * 64 + 32 + i0);
; #pragma unroll
;                     for (int bj = 0; bj < 2; ++bj) { const int head = (pn - 8) * 4 + bj * 2 + (wc >> 1);
;                         const f32x4 x1 = acc[ai][bj][m][0] * r, x2 = acc[ai][bj][m][1] * r;
;                         *(u32x2*)(qrow + head * 192 + 128 + i0) = pack4(x1 * cs - x2 * sn);
;                         *(u32x2*)(qrow + head * 192 + 160 + i0) = pack4(x2 * cs + x1 * sn); }
;                 }
.LBB0_736:
	v_or_b32_e32 v12, 32, v4
	v_subrev_u32_e32 v3, s62, v12
	v_lshl_add_u32 v3, v3, 2, 0
	v_add_u32_e32 v3, 0x21000, v3
	s_waitcnt lgkmcnt(0)
	ds_read_b32 v8, v3
	v_mov_b64_e32 v[10:11], s[18:19]
	v_mad_i64_i32 v[10:11], s[40:41], v12, s64, v[10:11]
	s_and_b64 vcc, exec, s[2:3]
	s_mov_b64 s[40:41], -1
	s_cbranch_vccnz .LBB0_738
	v_mov_b32_e32 v7, v165
	s_nop 0
	s_waitcnt lgkmcnt(0)
	v_pk_mul_f32 v[24:25], v[124:125], v[8:9] op_sel_hi:[1,0]
	v_pk_mul_f32 v[26:27], v[122:123], v[8:9] op_sel_hi:[1,0]
	v_pk_mul_f32 v[20:21], v[128:129], v[8:9] op_sel_hi:[1,0]
	v_pk_mul_f32 v[22:23], v[126:127], v[8:9] op_sel_hi:[1,0]
	s_mov_b32 s37, s17
	v_pk_mul_f32 v[28:29], v[120:121], v[8:9] op_sel_hi:[1,0]
	v_pk_mul_f32 v[30:31], v[118:119], v[8:9] op_sel_hi:[1,0]
	v_pk_mul_f32 v[32:33], v[116:117], v[8:9] op_sel_hi:[1,0]
	v_pk_mul_f32 v[130:131], v[114:115], v[8:9] op_sel_hi:[1,0]
	v_mov_b32_e32 v3, v165
	s_add_i32 s16, s36, 0x180
	v_lshl_add_u64 v[132:133], s[36:37], 1, v[10:11]
	v_lshl_add_u64 v[134:135], s[16:17], 1, v[10:11]
	v_lshl_add_u64 v[132:133], v[132:133], 0, v[2:3]
	s_mov_b64 s[40:41], 0
	v_lshl_add_u64 v[134:135], v[134:135], 0, v[2:3]
	s_waitcnt vmcnt(16)
	v_pk_mul_f32 v[136:137], v[24:25], v[224:225]
	v_pk_mul_f32 v[138:139], v[26:27], v[222:223]
	v_pk_mul_f32 v[140:141], v[20:21], v[224:225]
	v_pk_mul_f32 v[142:143], v[22:23], v[222:223]
	v_pk_mul_f32 v[144:145], v[32:33], v[224:225]
	v_pk_mul_f32 v[146:147], v[130:131], v[222:223]
	v_pk_mul_f32 v[14:15], v[28:29], v[224:225]
	v_pk_mul_f32 v[12:13], v[30:31], v[222:223]
	v_pk_fma_f32 v[20:21], v[20:21], v[228:229], v[136:137] neg_lo:[0,0,1] neg_hi:[0,0,1]
	v_pk_fma_f32 v[22:23], v[22:23], v[226:227], v[138:139] neg_lo:[0,0,1] neg_hi:[0,0,1]
	v_pk_fma_f32 v[24:25], v[24:25], v[228:229], v[140:141]
	v_pk_fma_f32 v[26:27], v[26:27], v[226:227], v[142:143]
	v_pk_fma_f32 v[28:29], v[28:29], v[228:229], v[144:145] neg_lo:[0,0,1] neg_hi:[0,0,1]
	v_pk_fma_f32 v[30:31], v[30:31], v[226:227], v[146:147] neg_lo:[0,0,1] neg_hi:[0,0,1]
	v_pk_fma_f32 v[14:15], v[32:33], v[228:229], v[14:15]
	v_pk_fma_f32 v[12:13], v[130:131], v[226:227], v[12:13]
	v_cvt_pk_bf16_f32 v16, v22, v23
	v_cvt_pk_bf16_f32 v17, v20, v21
	v_cvt_pk_bf16_f32 v18, v26, v27
	v_cvt_pk_bf16_f32 v19, v24, v25
	v_cvt_pk_bf16_f32 v20, v30, v31
	v_cvt_pk_bf16_f32 v21, v28, v29
	v_cvt_pk_bf16_f32 v12, v12, v13
	v_cvt_pk_bf16_f32 v13, v14, v15
	v_mov_b32_e32 v255, 0
	v_mov_b32_e32 v254, 0xb000
	v_lshl_add_u64 v[252:253], v[250:251], 0, v[254:255]
	global_load_dwordx4 v[222:225], v[252:253], off offset:128
	global_load_dwordx4 v[226:229], v[252:253], off
	global_store_dwordx2 v[132:133], v[16:17], off offset:256
	global_store_dwordx2 v[132:133], v[18:19], off offset:320
	global_store_dwordx2 v[134:135], v[20:21], off offset:256
	global_store_dwordx2 v[134:135], v[12:13], off offset:320

; __device__ __forceinline__ u32x2 pack4(f32x4 v) { u32x2 w; w.x = cvtpk(v[0], v[1]); w.y = cvtpk(v[2], v[3]); return w; }
;     __device__ __forceinline__ void operator()(const Acc& acc, const Unit& u, int wr, int wc, int fr, int fq) const {
;     ...
;                 } else {
;                     const int i0 = 16 * (wc & 1) + 4 * fq;
;                     const f32x4 cs = *(const f32x4*)(ropeM + (size_t)row * 64 + i0), sn = *(const f32x4*)(ropeM + (size_t)row * 64 + 32 + i0);
; #pragma unroll
;                     for (int bj = 0; bj < 2; ++bj) { const int head = (pn - 8) * 4 + bj * 2 + (wc >> 1);
;                         const f32x4 x1 = acc[ai][bj][m][0] * r, x2 = acc[ai][bj][m][1] * r;
;                         *(u32x2*)(qrow + head * 192 + 128 + i0) = pack4(x1 * cs - x2 * sn);
;                         *(u32x2*)(qrow + head * 192 + 160 + i0) = pack4(x2 * cs + x1 * sn); }
;                 }
.LBB0_740:
	v_or_b32_e32 v12, 48, v4
	v_subrev_u32_e32 v3, s62, v12
	v_lshl_add_u32 v3, v3, 2, 0
	v_add_u32_e32 v3, 0x21000, v3
	s_waitcnt lgkmcnt(0)
	ds_read_b32 v8, v3
	v_mov_b64_e32 v[10:11], s[18:19]
	v_mad_i64_i32 v[10:11], s[40:41], v12, s64, v[10:11]
	s_and_b64 vcc, exec, s[2:3]
	s_mov_b64 s[40:41], -1
	s_cbranch_vccnz .LBB0_742
	v_mov_b32_e32 v7, v165
	s_nop 0
	s_waitcnt lgkmcnt(0)
	v_pk_mul_f32 v[24:25], v[108:109], v[8:9] op_sel_hi:[1,0]
	v_pk_mul_f32 v[26:27], v[106:107], v[8:9] op_sel_hi:[1,0]
	v_pk_mul_f32 v[20:21], v[112:113], v[8:9] op_sel_hi:[1,0]
	v_pk_mul_f32 v[22:23], v[110:111], v[8:9] op_sel_hi:[1,0]
	s_mov_b32 s37, s17
	v_pk_mul_f32 v[28:29], v[104:105], v[8:9] op_sel_hi:[1,0]
	v_pk_mul_f32 v[30:31], v[102:103], v[8:9] op_sel_hi:[1,0]
	v_pk_mul_f32 v[32:33], v[100:101], v[8:9] op_sel_hi:[1,0]
	v_pk_mul_f32 v[114:115], v[98:99], v[8:9] op_sel_hi:[1,0]
	v_mov_b32_e32 v3, v165
	s_add_i32 s16, s36, 0x180
	v_lshl_add_u64 v[116:117], s[36:37], 1, v[10:11]
	v_lshl_add_u64 v[118:119], s[16:17], 1, v[10:11]
	v_lshl_add_u64 v[116:117], v[116:117], 0, v[2:3]
	s_mov_b64 s[40:41], 0
	v_lshl_add_u64 v[118:119], v[118:119], 0, v[2:3]
	s_waitcnt vmcnt(20)
	v_pk_mul_f32 v[120:121], v[24:25], v[232:233]
	v_pk_mul_f32 v[122:123], v[26:27], v[230:231]
	v_pk_mul_f32 v[124:125], v[20:21], v[232:233]
	v_pk_mul_f32 v[126:127], v[22:23], v[230:231]
	v_pk_mul_f32 v[128:129], v[32:33], v[232:233]
	v_pk_mul_f32 v[130:131], v[114:115], v[230:231]
	v_pk_mul_f32 v[14:15], v[28:29], v[232:233]
	v_pk_mul_f32 v[12:13], v[30:31], v[230:231]
	v_pk_fma_f32 v[20:21], v[20:21], v[236:237], v[120:121] neg_lo:[0,0,1] neg_hi:[0,0,1]
	v_pk_fma_f32 v[22:23], v[22:23], v[234:235], v[122:123] neg_lo:[0,0,1] neg_hi:[0,0,1]
	v_pk_fma_f32 v[24:25], v[24:25], v[236:237], v[124:125]
	v_pk_fma_f32 v[26:27], v[26:27], v[234:235], v[126:127]
	v_pk_fma_f32 v[28:29], v[28:29], v[236:237], v[128:129] neg_lo:[0,0,1] neg_hi:[0,0,1]
	v_pk_fma_f32 v[30:31], v[30:31], v[234:235], v[130:131] neg_lo:[0,0,1] neg_hi:[0,0,1]
	v_pk_fma_f32 v[14:15], v[32:33], v[236:237], v[14:15]
	v_pk_fma_f32 v[12:13], v[114:115], v[234:235], v[12:13]
	v_cvt_pk_bf16_f32 v16, v22, v23
	v_cvt_pk_bf16_f32 v17, v20, v21
	v_cvt_pk_bf16_f32 v18, v26, v27
	v_cvt_pk_bf16_f32 v19, v24, v25
	v_cvt_pk_bf16_f32 v20, v30, v31
	v_cvt_pk_bf16_f32 v21, v28, v29
	v_cvt_pk_bf16_f32 v12, v12, v13
	v_cvt_pk_bf16_f32 v13, v14, v15
	global_store_dwordx2 v[116:117], v[16:17], off offset:256
	global_store_dwordx2 v[116:117], v[18:19], off offset:320
	global_store_dwordx2 v[118:119], v[20:21], off offset:256
	global_store_dwordx2 v[118:119], v[12:13], off offset:320

; __device__ __forceinline__ u32x2 pack4(f32x4 v) { u32x2 w; w.x = cvtpk(v[0], v[1]); w.y = cvtpk(v[2], v[3]); return w; }
;     __device__ __forceinline__ void operator()(const Acc& acc, const Unit& u, int wr, int wc, int fr, int fq) const {
;     ...
;                 } else {
;                     const int i0 = 16 * (wc & 1) + 4 * fq;
;                     const f32x4 cs = *(const f32x4*)(ropeM + (size_t)row * 64 + i0), sn = *(const f32x4*)(ropeM + (size_t)row * 64 + 32 + i0);
; #pragma unroll
;                     for (int bj = 0; bj < 2; ++bj) { const int head = (pn - 8) * 4 + bj * 2 + (wc >> 1);
;                         const f32x4 x1 = acc[ai][bj][m][0] * r, x2 = acc[ai][bj][m][1] * r;
;                         *(u32x2*)(qrow + head * 192 + 128 + i0) = pack4(x1 * cs - x2 * sn);
;                         *(u32x2*)(qrow + head * 192 + 160 + i0) = pack4(x2 * cs + x1 * sn); }
;                 }
.LBB0_744:
	v_add_u32_e32 v12, 0x80, v4
	v_subrev_u32_e32 v3, s62, v12
	v_lshl_add_u32 v3, v3, 2, 0
	v_add_u32_e32 v3, 0x21000, v3
	s_waitcnt lgkmcnt(0)
	ds_read_b32 v8, v3
	v_mov_b64_e32 v[10:11], s[18:19]
	v_mad_i64_i32 v[10:11], s[40:41], v12, s64, v[10:11]
	s_and_b64 vcc, exec, s[2:3]
	s_mov_b64 s[40:41], -1
	s_cbranch_vccnz .LBB0_746
	v_mov_b32_e32 v7, v165
	s_nop 0
	s_waitcnt lgkmcnt(0)
	v_pk_mul_f32 v[24:25], v[92:93], v[8:9] op_sel_hi:[1,0]
	v_pk_mul_f32 v[26:27], v[90:91], v[8:9] op_sel_hi:[1,0]
	v_pk_mul_f32 v[20:21], v[96:97], v[8:9] op_sel_hi:[1,0]
	v_pk_mul_f32 v[22:23], v[94:95], v[8:9] op_sel_hi:[1,0]
	s_mov_b32 s37, s17
	v_pk_mul_f32 v[28:29], v[88:89], v[8:9] op_sel_hi:[1,0]
	v_pk_mul_f32 v[30:31], v[86:87], v[8:9] op_sel_hi:[1,0]
	v_pk_mul_f32 v[32:33], v[84:85], v[8:9] op_sel_hi:[1,0]
	v_pk_mul_f32 v[98:99], v[82:83], v[8:9] op_sel_hi:[1,0]
	v_mov_b32_e32 v3, v165
	s_add_i32 s16, s36, 0x180
	v_lshl_add_u64 v[100:101], s[36:37], 1, v[10:11]
	v_lshl_add_u64 v[102:103], s[16:17], 1, v[10:11]
	v_lshl_add_u64 v[100:101], v[100:101], 0, v[2:3]
	s_mov_b64 s[40:41], 0
	v_lshl_add_u64 v[102:103], v[102:103], 0, v[2:3]
	s_waitcnt vmcnt(22)
	v_pk_mul_f32 v[104:105], v[24:25], v[240:241]
	v_pk_mul_f32 v[106:107], v[26:27], v[238:239]
	v_pk_mul_f32 v[108:109], v[20:21], v[240:241]
	v_pk_mul_f32 v[110:111], v[22:23], v[238:239]
	v_pk_mul_f32 v[112:113], v[32:33], v[240:241]
	v_pk_mul_f32 v[114:115], v[98:99], v[238:239]
	v_pk_mul_f32 v[14:15], v[28:29], v[240:241]
	v_pk_mul_f32 v[12:13], v[30:31], v[238:239]
	v_pk_fma_f32 v[20:21], v[20:21], v[248:249], v[104:105] neg_lo:[0,0,1] neg_hi:[0,0,1]
	v_pk_fma_f32 v[22:23], v[22:23], v[246:247], v[106:107] neg_lo:[0,0,1] neg_hi:[0,0,1]
	v_pk_fma_f32 v[24:25], v[24:25], v[248:249], v[108:109]
	v_pk_fma_f32 v[26:27], v[26:27], v[246:247], v[110:111]
	v_pk_fma_f32 v[28:29], v[28:29], v[248:249], v[112:113] neg_lo:[0,0,1] neg_hi:[0,0,1]
	v_pk_fma_f32 v[30:31], v[30:31], v[246:247], v[114:115] neg_lo:[0,0,1] neg_hi:[0,0,1]
	v_pk_fma_f32 v[14:15], v[32:33], v[248:249], v[14:15]
	v_pk_fma_f32 v[12:13], v[98:99], v[246:247], v[12:13]
	v_cvt_pk_bf16_f32 v16, v22, v23
	v_cvt_pk_bf16_f32 v17, v20, v21
	v_cvt_pk_bf16_f32 v18, v26, v27
	v_cvt_pk_bf16_f32 v19, v24, v25
	v_cvt_pk_bf16_f32 v20, v30, v31
	v_cvt_pk_bf16_f32 v21, v28, v29
	v_cvt_pk_bf16_f32 v12, v12, v13
	v_cvt_pk_bf16_f32 v13, v14, v15
	global_store_dwordx2 v[100:101], v[16:17], off offset:256
	global_store_dwordx2 v[100:101], v[18:19], off offset:320
	global_store_dwordx2 v[102:103], v[20:21], off offset:256
	global_store_dwordx2 v[102:103], v[12:13], off offset:320

; __device__ __forceinline__ u32x2 pack4(f32x4 v) { u32x2 w; w.x = cvtpk(v[0], v[1]); w.y = cvtpk(v[2], v[3]); return w; }
;     __device__ __forceinline__ void operator()(const Acc& acc, const Unit& u, int wr, int wc, int fr, int fq) const {
;     ...
;                 } else {
;                     const int i0 = 16 * (wc & 1) + 4 * fq;
;                     const f32x4 cs = *(const f32x4*)(ropeM + (size_t)row * 64 + i0), sn = *(const f32x4*)(ropeM + (size_t)row * 64 + 32 + i0);
; #pragma unroll
;                     for (int bj = 0; bj < 2; ++bj) { const int head = (pn - 8) * 4 + bj * 2 + (wc >> 1);
;                         const f32x4 x1 = acc[ai][bj][m][0] * r, x2 = acc[ai][bj][m][1] * r;
;                         *(u32x2*)(qrow + head * 192 + 128 + i0) = pack4(x1 * cs - x2 * sn);
;                         *(u32x2*)(qrow + head * 192 + 160 + i0) = pack4(x2 * cs + x1 * sn); }
;                 }
.LBB0_748:
	v_add_u32_e32 v12, 0x90, v4
	v_subrev_u32_e32 v3, s62, v12
	v_lshl_add_u32 v3, v3, 2, 0
	v_add_u32_e32 v3, 0x21000, v3
	s_waitcnt lgkmcnt(0)
	ds_read_b32 v8, v3
	v_mov_b64_e32 v[10:11], s[18:19]
	v_mad_i64_i32 v[10:11], s[40:41], v12, s64, v[10:11]
	s_and_b64 vcc, exec, s[2:3]
	s_mov_b64 s[40:41], -1
	s_cbranch_vccnz .LBB0_750
	v_mov_b32_e32 v7, v165
	s_nop 0
	s_waitcnt lgkmcnt(0)
	v_pk_mul_f32 v[24:25], v[76:77], v[8:9] op_sel_hi:[1,0]
	v_pk_mul_f32 v[26:27], v[74:75], v[8:9] op_sel_hi:[1,0]
	v_pk_mul_f32 v[20:21], v[80:81], v[8:9] op_sel_hi:[1,0]
	v_pk_mul_f32 v[22:23], v[78:79], v[8:9] op_sel_hi:[1,0]
	s_mov_b32 s37, s17
	v_pk_mul_f32 v[28:29], v[72:73], v[8:9] op_sel_hi:[1,0]
	v_pk_mul_f32 v[30:31], v[70:71], v[8:9] op_sel_hi:[1,0]
	v_pk_mul_f32 v[32:33], v[68:69], v[8:9] op_sel_hi:[1,0]
	v_pk_mul_f32 v[82:83], v[66:67], v[8:9] op_sel_hi:[1,0]
	v_mov_b32_e32 v3, v165
	s_add_i32 s16, s36, 0x180
	v_lshl_add_u64 v[84:85], s[36:37], 1, v[10:11]
	v_lshl_add_u64 v[86:87], s[16:17], 1, v[10:11]
	v_lshl_add_u64 v[84:85], v[84:85], 0, v[2:3]
	s_mov_b64 s[40:41], 0
	v_lshl_add_u64 v[86:87], v[86:87], 0, v[2:3]
	s_waitcnt vmcnt(24)
	v_pk_mul_f32 v[88:89], v[24:25], v[208:209]
	v_pk_mul_f32 v[90:91], v[26:27], v[206:207]
	v_pk_mul_f32 v[92:93], v[20:21], v[208:209]
	v_pk_mul_f32 v[94:95], v[22:23], v[206:207]
	v_pk_mul_f32 v[96:97], v[32:33], v[208:209]
	v_pk_mul_f32 v[98:99], v[82:83], v[206:207]
	v_pk_mul_f32 v[14:15], v[28:29], v[208:209]
	v_pk_mul_f32 v[12:13], v[30:31], v[206:207]
	v_pk_fma_f32 v[20:21], v[20:21], v[212:213], v[88:89] neg_lo:[0,0,1] neg_hi:[0,0,1]
	v_pk_fma_f32 v[22:23], v[22:23], v[210:211], v[90:91] neg_lo:[0,0,1] neg_hi:[0,0,1]
	v_pk_fma_f32 v[24:25], v[24:25], v[212:213], v[92:93]
	v_pk_fma_f32 v[26:27], v[26:27], v[210:211], v[94:95]
	v_pk_fma_f32 v[28:29], v[28:29], v[212:213], v[96:97] neg_lo:[0,0,1] neg_hi:[0,0,1]
	v_pk_fma_f32 v[30:31], v[30:31], v[210:211], v[98:99] neg_lo:[0,0,1] neg_hi:[0,0,1]
	v_pk_fma_f32 v[14:15], v[32:33], v[212:213], v[14:15]
	v_pk_fma_f32 v[12:13], v[82:83], v[210:211], v[12:13]
	v_cvt_pk_bf16_f32 v16, v22, v23
	v_cvt_pk_bf16_f32 v17, v20, v21
	v_cvt_pk_bf16_f32 v18, v26, v27
	v_cvt_pk_bf16_f32 v19, v24, v25
	v_cvt_pk_bf16_f32 v20, v30, v31
	v_cvt_pk_bf16_f32 v21, v28, v29
	v_cvt_pk_bf16_f32 v12, v12, v13
	v_cvt_pk_bf16_f32 v13, v14, v15
	global_store_dwordx2 v[84:85], v[16:17], off offset:256
	global_store_dwordx2 v[84:85], v[18:19], off offset:320
	global_store_dwordx2 v[86:87], v[20:21], off offset:256
	global_store_dwordx2 v[86:87], v[12:13], off offset:320

; __device__ __forceinline__ u32x2 pack4(f32x4 v) { u32x2 w; w.x = cvtpk(v[0], v[1]); w.y = cvtpk(v[2], v[3]); return w; }
;     __device__ __forceinline__ void operator()(const Acc& acc, const Unit& u, int wr, int wc, int fr, int fq) const {
;     ...
;                 } else {
;                     const int i0 = 16 * (wc & 1) + 4 * fq;
;                     const f32x4 cs = *(const f32x4*)(ropeM + (size_t)row * 64 + i0), sn = *(const f32x4*)(ropeM + (size_t)row * 64 + 32 + i0);
; #pragma unroll
;                     for (int bj = 0; bj < 2; ++bj) { const int head = (pn - 8) * 4 + bj * 2 + (wc >> 1);
;                         const f32x4 x1 = acc[ai][bj][m][0] * r, x2 = acc[ai][bj][m][1] * r;
;                         *(u32x2*)(qrow + head * 192 + 128 + i0) = pack4(x1 * cs - x2 * sn);
;                         *(u32x2*)(qrow + head * 192 + 160 + i0) = pack4(x2 * cs + x1 * sn); }
;                 }
.LBB0_752:
	v_add_u32_e32 v12, 0xa0, v4
	v_subrev_u32_e32 v3, s62, v12
	v_lshl_add_u32 v3, v3, 2, 0
	v_add_u32_e32 v3, 0x21000, v3
	s_waitcnt lgkmcnt(0)
	ds_read_b32 v8, v3
	v_mov_b64_e32 v[10:11], s[18:19]
	v_mad_i64_i32 v[10:11], s[40:41], v12, s64, v[10:11]
	s_and_b64 vcc, exec, s[2:3]
	s_mov_b64 s[40:41], -1
	s_cbranch_vccnz .LBB0_754
	v_mov_b32_e32 v7, v165
	s_nop 0
	s_waitcnt lgkmcnt(0)
	v_pk_mul_f32 v[24:25], v[60:61], v[8:9] op_sel_hi:[1,0]
	v_pk_mul_f32 v[26:27], v[58:59], v[8:9] op_sel_hi:[1,0]
	v_pk_mul_f32 v[20:21], v[64:65], v[8:9] op_sel_hi:[1,0]
	v_pk_mul_f32 v[22:23], v[62:63], v[8:9] op_sel_hi:[1,0]
	s_mov_b32 s37, s17
	v_pk_mul_f32 v[28:29], v[56:57], v[8:9] op_sel_hi:[1,0]
	v_pk_mul_f32 v[30:31], v[54:55], v[8:9] op_sel_hi:[1,0]
	v_pk_mul_f32 v[32:33], v[52:53], v[8:9] op_sel_hi:[1,0]
	v_pk_mul_f32 v[66:67], v[50:51], v[8:9] op_sel_hi:[1,0]
	v_mov_b32_e32 v3, v165
	s_add_i32 s16, s36, 0x180
	v_lshl_add_u64 v[68:69], s[36:37], 1, v[10:11]
	v_lshl_add_u64 v[70:71], s[16:17], 1, v[10:11]
	v_lshl_add_u64 v[68:69], v[68:69], 0, v[2:3]
	s_mov_b64 s[40:41], 0
	v_lshl_add_u64 v[70:71], v[70:71], 0, v[2:3]
	s_waitcnt vmcnt(22)
	v_pk_mul_f32 v[72:73], v[24:25], v[216:217]
	v_pk_mul_f32 v[74:75], v[26:27], v[214:215]
	v_pk_mul_f32 v[76:77], v[20:21], v[216:217]
	v_pk_mul_f32 v[78:79], v[22:23], v[214:215]
	v_pk_mul_f32 v[80:81], v[32:33], v[216:217]
	v_pk_mul_f32 v[82:83], v[66:67], v[214:215]
	v_pk_mul_f32 v[14:15], v[28:29], v[216:217]
	v_pk_mul_f32 v[12:13], v[30:31], v[214:215]
	v_pk_fma_f32 v[20:21], v[20:21], v[220:221], v[72:73] neg_lo:[0,0,1] neg_hi:[0,0,1]
	v_pk_fma_f32 v[22:23], v[22:23], v[218:219], v[74:75] neg_lo:[0,0,1] neg_hi:[0,0,1]
	v_pk_fma_f32 v[24:25], v[24:25], v[220:221], v[76:77]
	v_pk_fma_f32 v[26:27], v[26:27], v[218:219], v[78:79]
	v_pk_fma_f32 v[28:29], v[28:29], v[220:221], v[80:81] neg_lo:[0,0,1] neg_hi:[0,0,1]
	v_pk_fma_f32 v[30:31], v[30:31], v[218:219], v[82:83] neg_lo:[0,0,1] neg_hi:[0,0,1]
	v_pk_fma_f32 v[14:15], v[32:33], v[220:221], v[14:15]
	v_pk_fma_f32 v[12:13], v[66:67], v[218:219], v[12:13]
	v_cvt_pk_bf16_f32 v16, v22, v23
	v_cvt_pk_bf16_f32 v17, v20, v21
	v_cvt_pk_bf16_f32 v18, v26, v27
	v_cvt_pk_bf16_f32 v19, v24, v25
	v_cvt_pk_bf16_f32 v20, v30, v31
	v_cvt_pk_bf16_f32 v21, v28, v29
	v_cvt_pk_bf16_f32 v12, v12, v13
	v_cvt_pk_bf16_f32 v13, v14, v15
	global_store_dwordx2 v[68:69], v[16:17], off offset:256
	global_store_dwordx2 v[68:69], v[18:19], off offset:320
	global_store_dwordx2 v[70:71], v[20:21], off offset:256
	global_store_dwordx2 v[70:71], v[12:13], off offset:320

; __device__ __forceinline__ u32x2 pack4(f32x4 v) { u32x2 w; w.x = cvtpk(v[0], v[1]); w.y = cvtpk(v[2], v[3]); return w; }
;     __device__ __forceinline__ void operator()(const Acc& acc, const Unit& u, int wr, int wc, int fr, int fq) const {
;     ...
;                 } else {
;                     const int i0 = 16 * (wc & 1) + 4 * fq;
;                     const f32x4 cs = *(const f32x4*)(ropeM + (size_t)row * 64 + i0), sn = *(const f32x4*)(ropeM + (size_t)row * 64 + 32 + i0);
; #pragma unroll
;                     for (int bj = 0; bj < 2; ++bj) { const int head = (pn - 8) * 4 + bj * 2 + (wc >> 1);
;                         const f32x4 x1 = acc[ai][bj][m][0] * r, x2 = acc[ai][bj][m][1] * r;
;                         *(u32x2*)(qrow + head * 192 + 128 + i0) = pack4(x1 * cs - x2 * sn);
;                         *(u32x2*)(qrow + head * 192 + 160 + i0) = pack4(x2 * cs + x1 * sn); }
;                 }
.LBB0_756:
	v_add_u32_e32 v10, 0xb0, v4
	v_subrev_u32_e32 v3, s62, v10
	v_lshl_add_u32 v3, v3, 2, 0
	v_add_u32_e32 v3, 0x21000, v3
	ds_read_b32 v4, v3
	s_waitcnt lgkmcnt(0)
	v_mov_b64_e32 v[8:9], s[18:19]
	v_mad_i64_i32 v[8:9], s[40:41], v10, s64, v[8:9]
	s_and_b64 vcc, exec, s[2:3]
	s_mov_b64 s[2:3], -1
	s_cbranch_vccnz .LBB0_758
	v_mov_b32_e32 v7, v165
	s_mov_b32 s37, s17
	s_add_i32 s16, s36, 0x180
	v_pk_mul_f32 v[20:21], v[44:45], v[4:5] op_sel_hi:[1,0]
	v_pk_mul_f32 v[22:23], v[42:43], v[4:5] op_sel_hi:[1,0]
	v_mov_b32_e32 v3, v165
	v_lshl_add_u64 v[32:33], s[36:37], 1, v[8:9]
	v_lshl_add_u64 v[50:51], s[16:17], 1, v[8:9]
	v_pk_mul_f32 v[6:7], v[48:49], v[4:5] op_sel_hi:[1,0]
	v_pk_mul_f32 v[18:19], v[46:47], v[4:5] op_sel_hi:[1,0]
	v_pk_mul_f32 v[24:25], v[40:41], v[4:5] op_sel_hi:[1,0]
	v_pk_mul_f32 v[26:27], v[38:39], v[4:5] op_sel_hi:[1,0]
	v_pk_mul_f32 v[28:29], v[36:37], v[4:5] op_sel_hi:[1,0]
	v_pk_mul_f32 v[30:31], v[34:35], v[4:5] op_sel_hi:[1,0]
	v_lshl_add_u64 v[32:33], v[32:33], 0, v[2:3]
	v_lshl_add_u64 v[2:3], v[50:51], 0, v[2:3]
	s_mov_b64 s[2:3], 0
	s_waitcnt vmcnt(20)
	v_pk_mul_f32 v[50:51], v[20:21], v[224:225]
	v_pk_mul_f32 v[52:53], v[22:23], v[222:223]
	v_pk_mul_f32 v[54:55], v[6:7], v[224:225]
	v_pk_mul_f32 v[56:57], v[18:19], v[222:223]
	v_pk_mul_f32 v[58:59], v[28:29], v[224:225]
	v_pk_mul_f32 v[60:61], v[30:31], v[222:223]
	v_pk_mul_f32 v[12:13], v[24:25], v[224:225]
	v_pk_mul_f32 v[10:11], v[26:27], v[222:223]
	v_pk_fma_f32 v[6:7], v[6:7], v[228:229], v[50:51] neg_lo:[0,0,1] neg_hi:[0,0,1]
	v_pk_fma_f32 v[18:19], v[18:19], v[226:227], v[52:53] neg_lo:[0,0,1] neg_hi:[0,0,1]
	v_pk_fma_f32 v[20:21], v[20:21], v[228:229], v[54:55]
	v_pk_fma_f32 v[22:23], v[22:23], v[226:227], v[56:57]
	v_pk_fma_f32 v[24:25], v[24:25], v[228:229], v[58:59] neg_lo:[0,0,1] neg_hi:[0,0,1]
	v_pk_fma_f32 v[26:27], v[26:27], v[226:227], v[60:61] neg_lo:[0,0,1] neg_hi:[0,0,1]
	v_pk_fma_f32 v[12:13], v[28:29], v[228:229], v[12:13]
	v_pk_fma_f32 v[10:11], v[30:31], v[226:227], v[10:11]
	v_cvt_pk_bf16_f32 v14, v18, v19
	v_cvt_pk_bf16_f32 v15, v6, v7
	v_cvt_pk_bf16_f32 v6, v22, v23
	v_cvt_pk_bf16_f32 v7, v20, v21
	v_cvt_pk_bf16_f32 v16, v26, v27
	v_cvt_pk_bf16_f32 v17, v24, v25
	v_cvt_pk_bf16_f32 v10, v10, v11
	v_cvt_pk_bf16_f32 v11, v12, v13
	global_store_dwordx2 v[32:33], v[14:15], off offset:256
	global_store_dwordx2 v[32:33], v[6:7], off offset:320
	global_store_dwordx2 v[2:3], v[16:17], off offset:256
	global_store_dwordx2 v[2:3], v[10:11], off offset:320
